# P8 and P12: sample K-piece before the prompt tile in both split GEMM phases
# speedup vs baseline: 1.0020x; 1.0020x over previous
; #define PG8_STAGE(bufoff, gbase, voff) do { _Pragma("unroll") for (int _i = 0; _i < 2; ++_i) \
;         __builtin_amdgcn_global_load_lds((const unsigned*)((const char*)(gbase) + (voff)[_i]), (LAS unsigned*)(lds + (bufoff) + ldsw + _i * 8192), 16, 0, 0); } while (0)
; template <class Epi, class S_t>
; __device__ __forceinline__ void gemm_phase(LAS unsigned char* lds, int lda, int ldb, const S_t& S, const Epi& E) {
;     ...
;     for (int i = 0; i < 2; ++i) { int R, C; stage_rc(tid * 16 + i * 8192, R, C); const int Rb = Epi::PERM ? ((R & ~31) + perm32(R & 31)) : R;
;         voffA[i] = (unsigned)(R * lda + C) * 2u; voffB[i] = (unsigned)(Rb * ldb + C) * 2u; }
;     const size_t kstep = (size_t)(BK * 2);
;     const size_t hstepA = (size_t)HALF * lda * 2, hstepB = (size_t)HALF * ldb * 2;
;     const unsigned ldsw = (unsigned)wid * 1024u;
;     const int aoff = lds_byte(wr * 64 + fr, fq * 8), boff = lds_byte(wc * 32 + fr, fq * 8);
;     ...
;     Unit cur, nxt; int ui = 0;
;     if (!S.next(0, cur)) return;
;     f32x4 acc[2][2][4][2];
; #pragma unroll
;     for (int a = 0; a < 2; ++a)
; #pragma unroll
;         for (int b = 0; b < 2; ++b)
; #pragma unroll
;             for (int m = 0; m < 4; ++m)
; #pragma unroll
;                 for (int n = 0; n < 2; ++n) acc[a][b][m][n] = (f32x4){0.f, 0.f, 0.f, 0.f};
;     bf16x8 At[4][2], B0[2][2], B1[2][2];
;     const char* cA = cur.A; const char* cB = cur.B;
;     PG8_STAGE(PG8_SB(0, 0), cB, voffB); PG8_STAGE(PG8_SA(0, 0), cA, voffA); PG8_STAGE(PG8_SB(0, 1), cB + hstepB, voffB); PG8_STAGE(PG8_SA(0, 1), cA + hstepA, voffA);
;     if (wr == 1) PG8_BAR;
;     PG8_WAIT_V(4); PG8_BAR;
;     PG8_STAGE(PG8_SB(1, 0), cB + kstep, voffB); PG8_STAGE(PG8_SA(1, 0), cA + kstep, voffA); PG8_STAGE(PG8_SB(1, 1), cB + hstepB + kstep, voffB);
;     PG8_WAIT_V(6); PG8_BAR;
;     __device__ __forceinline__ bool next(int i, Unit& u) const {
;     ...
;         const int tile = base.c >> 3, kz = base.c & 7;
;         if (kz < kz_lo || kz >= kz_hi) return false;
;         const int k = kz - kz_lo; int koff, nt;
;         if (mode == 0) { koff = k * ntp; nt = ntp; } else { koff = k < 4 ? 6 * k : 24 + 4 * (k - 4); nt = k < 4 ? 6 : 4; }
;         u.pm = 32 + (tile >> 3); u.pn = tile & 7; u.tag = 1 + kz; u.nt = nt;
;         u.A = base.A + (size_t)u.pm * base.a_tile + (size_t)koff * 128; u.B = base.B + (size_t)u.pn * base.b_tile + (size_t)koff * 128; return true;
.LBB0_1375:
	v_ashrrev_i32_e32 v1, 31, v212
	v_lshrrev_b32_e32 v1, 26, v1
	v_add_u32_e32 v1, v212, v1
	v_ashrrev_i32_e32 v8, 6, v1
	v_bfe_i32 v1, v212, 27, 1
	v_lshlrev_b32_e32 v0, 4, v212
	v_lshrrev_b32_e32 v1, 22, v1
	v_add_u32_e32 v1, v0, v1
	v_and_b32_e32 v1, 0xfffffc00, v1
	v_sub_u32_e32 v1, v0, v1
	v_lshrrev_b32_e32 v2, 4, v1
	v_bitop3_b32 v1, v2, v1, 32 bitop3:0x6c
	v_ashrrev_i32_e32 v3, 31, v1
	v_lshrrev_b32_e32 v3, 26, v3
	v_lshlrev_b32_e32 v2, 3, v8
	v_add_u32_e32 v3, v1, v3
	v_and_b32_e32 v2, -16, v2
	v_ashrrev_i32_e32 v9, 6, v3
	v_and_b32_e32 v3, 0xc0, v3
	v_add_u32_e32 v2, v9, v2
	v_lshlrev_b32_e32 v4, 5, v8
	v_sub_u32_e32 v1, v1, v3
	v_mov_b32_e32 v3, 1
	v_and_b32_e32 v10, 32, v4
	v_ashrrev_i16_sdwa v1, v3, sext(v1) dst_sel:DWORD dst_unused:UNUSED_PAD src0_sel:DWORD src1_sel:BYTE_0
	v_lshlrev_b32_e32 v4, 1, v2
	v_lshrrev_b32_e32 v5, 2, v2
	v_and_b32_e32 v6, 3, v9
	s_mov_b32 s4, 0x1fffe0
	v_bfe_i32 v11, v1, 0, 16
	v_and_b32_e32 v4, 24, v4
	v_and_b32_e32 v5, 4, v5
	v_and_or_b32 v6, v2, s4, v6
	s_movk_i32 s12, 0x1800
	v_add_u32_e32 v1, v10, v11
	v_or3_b32 v4, v6, v5, v4
	v_mul_lo_u32 v2, v2, s12
	v_add_lshl_u32 v128, v1, v2, 1
	v_mul_u32_u24_e32 v2, 0x1800, v4
	v_add_u32_e32 v0, 0x2000, v0
	s_add_u32 s0, s84, 0xe00000
	v_add_lshl_u32 v130, v2, v1, 1
	v_ashrrev_i32_e32 v1, 31, v0
	s_addc_u32 s1, s85, 0
	v_lshrrev_b32_e32 v1, 22, v1
	s_add_i32 s3, s3, s5
	v_add_u32_e32 v1, v0, v1
	s_ashr_i32 s5, s3, 31
	v_ashrrev_i32_e32 v12, 10, v1
	s_lshr_b32 s5, s5, 26
	v_mul_i32_i24_e32 v1, 0x400, v12
	s_add_i32 s5, s3, s5
	v_sub_u32_e32 v0, v0, v1
	s_ashr_i32 s9, s5, 6
	s_and_b32 s5, s5, 0xffc0
	v_lshrrev_b32_e32 v1, 4, v0
	s_sub_i32 s3, s3, s5
	v_bitop3_b32 v0, v1, v0, 32 bitop3:0x6c
	s_bfe_i32 s5, s3, 0x80000
	v_ashrrev_i32_e32 v2, 31, v0
	s_bfe_u32 s5, s5, 0x3000c
	v_lshrrev_b32_e32 v2, 26, v2
	s_add_i32 s5, s3, s5
	v_lshlrev_b32_e32 v1, 3, v12
	v_add_u32_e32 v2, v0, v2
	s_lshl_b32 s10, s9, 3
	s_bfe_i32 s9, s5, 0x80000
	s_and_b32 s5, s5, 0xf8
	v_and_b32_e32 v1, -16, v1
	v_ashrrev_i32_e32 v13, 6, v2
	v_lshlrev_b32_e32 v4, 5, v12
	s_sub_i32 s3, s3, s5
	v_add_u32_e32 v1, v13, v1
	v_and_b32_e32 v14, 32, v4
	v_and_b32_e32 v4, 3, v13
	s_sext_i32_i8 s3, s3
	v_and_or_b32 v4, v1, s4, v4
	s_ashr_i32 s4, s16, 6
	s_sext_i32_i16 s11, s9
	s_add_i32 s67, s10, s3
	s_ashr_i32 s8, s16, 8
	s_lshl_b32 s17, s4, 10
	s_lshr_b32 s9, s11, 3
	s_mul_i32 s5, s67, 0x300000
	v_and_b32_e32 v2, 0xc0, v2
	s_mul_hi_i32 s3, s67, 0x300000
	s_add_u32 s46, s40, s5
	v_sub_u32_e32 v0, v0, v2
	s_addc_u32 s47, s41, s3
	s_ashr_i32 s3, s11, 3
	v_ashrrev_i16_sdwa v0, v3, sext(v0) dst_sel:DWORD dst_unused:UNUSED_PAD src0_sel:DWORD src1_sel:BYTE_0
	v_lshlrev_b32_e32 v2, 1, v1
	v_lshrrev_b32_e32 v3, 2, v1
	s_mul_hi_i32 s5, s3, 0x300000
	s_mul_i32 s3, s3, 0x300000
	v_bfe_i32 v15, v0, 0, 16
	v_and_b32_e32 v2, 24, v2
	v_and_b32_e32 v3, 4, v3
	s_add_u32 s48, s0, s3
	v_add_u32_e32 v0, v14, v15
	v_or3_b32 v2, v4, v3, v2
	v_mul_lo_u32 v1, v1, s12
	s_addc_u32 s49, s1, s5
	s_mov_b64 s[98:99], s[46:47]
	s_mov_b64 s[100:101], s[48:49]
	v_readlane_b32 s10, v255, 14
	s_ashr_i32 s11, s2, 6
	s_add_i32 s11, s11, 32
	s_mul_i32 s3, s11, 0x300000
	s_mul_hi_i32 s5, s11, 0x300000
	s_mul_i32 s10, s10, 0x600
	s_add_u32 s46, s40, s3
	s_addc_u32 s47, s41, s5
	s_add_u32 s46, s46, s10
	s_addc_u32 s47, s47, 0
	s_bfe_u32 s11, s2, 0x30003
	s_mul_i32 s3, s11, 0x300000
	s_add_u32 s48, s0, s3
	s_addc_u32 s49, s1, 0
	s_add_u32 s48, s48, s10
	s_addc_u32 s49, s49, 0
	s_add_i32 s20, s17, 0
	v_add_lshl_u32 v132, v0, v1, 1
	v_mul_u32_u24_e32 v1, 0x1800, v2
	s_add_i32 m0, s20, 0x10000
	v_add_lshl_u32 v134, v1, v0, 1
	global_load_lds_dwordx4 v130, s[48:49]
	s_add_i32 m0, s20, 0x12000
	s_add_i32 s21, s20, 0x2000
	global_load_lds_dwordx4 v134, s[48:49]
	s_mov_b32 m0, s20
	s_add_u32 s10, s48, 0x180000
	global_load_lds_dwordx4 v128, s[46:47]
	s_mov_b32 m0, s21
	s_addc_u32 s11, s49, 0
	global_load_lds_dwordx4 v132, s[46:47]
	s_add_i32 m0, s20, 0x14000
	v_mov_b32_e32 v131, 0
	global_load_lds_dwordx4 v130, s[10:11]
	s_add_i32 m0, s20, 0x16000
	v_mov_b32_e32 v135, v131
	global_load_lds_dwordx4 v134, s[10:11]
	s_add_u32 s10, s46, 0x180000
	s_addc_u32 s11, s47, 0
	s_add_i32 s35, s20, 0x4000
	s_mov_b32 m0, s35
	s_add_i32 s54, s20, 0x6000
	global_load_lds_dwordx4 v128, s[10:11]
	s_mov_b32 m0, s54
	v_mov_b32_e32 v129, v131
	global_load_lds_dwordx4 v132, s[10:11]
	v_mov_b32_e32 v133, v131
	s_mov_b32 s3, 0
	v_lshl_add_u64 v[6:7], s[48:49], 0, v[130:131]
	v_lshl_add_u64 v[4:5], s[48:49], 0, v[134:135]
	v_lshl_add_u64 v[2:3], s[46:47], 0, v[128:129]
	s_cmp_lg_u32 s8, 1
	v_lshl_add_u64 v[0:1], s[46:47], 0, v[132:133]
	s_cbranch_scc1 .LBB0_1377
	s_barrier
; #define PG8_STAGE(bufoff, gbase, voff) do { _Pragma("unroll") for (int _i = 0; _i < 2; ++_i) \
;         __builtin_amdgcn_global_load_lds((const unsigned*)((const char*)(gbase) + (voff)[_i]), (LAS unsigned*)(lds + (bufoff) + ldsw + _i * 8192), 16, 0, 0); } while (0)
; #define PG8_WAIT_V(n) asm volatile("s_waitcnt vmcnt(" #n ")" ::: "memory")
; #define PG8_BAR __builtin_amdgcn_s_barrier()
; template <class Epi, class S_t>
; __device__ __forceinline__ void gemm_phase(LAS unsigned char* lds, int lda, int ldb, const S_t& S, const Epi& E) {
;     ...
;     PG8_STAGE(PG8_SB(1, 0), cB + kstep, voffB); PG8_STAGE(PG8_SA(1, 0), cA + kstep, voffA); PG8_STAGE(PG8_SB(1, 1), cB + hstepB + kstep, voffB);
;     PG8_WAIT_V(6); PG8_BAR;
;     for (;;) {
;         const bool has_next = S.next(ui + 1, nxt);
;         const char* nA = has_next ? nxt.A : cA; const char* nB = has_next ? nxt.B : cB;
;         const int nt = cur.nt;
.LBB0_1377:
	s_lshl_b32 s4, s4, 5
	s_and_b32 s18, s4, 0x60
	s_mov_b64 s[4:5], 0x80
	s_add_i32 m0, s20, 0x18000
	v_lshl_add_u64 v[6:7], v[6:7], 0, s[4:5]
	s_lshl_b32 s13, s8, 13
	s_lshl_b32 s14, s18, 7
	s_waitcnt vmcnt(4)
	s_barrier
	global_load_lds_dwordx4 v[6:7], off
	v_lshl_add_u64 v[4:5], v[4:5], 0, s[4:5]
	s_add_i32 m0, s20, 0x1a000
	s_add_i32 s55, s20, 0x8000
	s_add_i32 s56, s20, 0xa000
	global_load_lds_dwordx4 v[4:5], off
	v_lshl_add_u64 v[2:3], v[2:3], 0, s[4:5]
	s_mov_b32 m0, s55
	s_add_u32 s10, s48, 0x180080
	global_load_lds_dwordx4 v[2:3], off
	v_lshl_add_u64 v[0:1], v[0:1], 0, s[4:5]
	s_mov_b32 m0, s56
	s_addc_u32 s11, s49, 0
	global_load_lds_dwordx4 v[0:1], off
	s_add_i32 m0, s20, 0x1c000
	v_lshl_add_u64 v[0:1], s[10:11], 0, v[130:131]
	global_load_lds_dwordx4 v[0:1], off
	v_lshl_add_u64 v[0:1], s[10:11], 0, v[134:135]
	s_add_i32 m0, s20, 0x1e000
	s_sext_i32_i8 s68, s9
	global_load_lds_dwordx4 v[0:1], off
	v_and_b32_e32 v0, 15, v212
	v_lshl_or_b32 v142, s8, 6, v0
	s_ashr_i32 s8, s2, 6
	s_add_i32 s57, s8, 32
	v_readlane_b32 s9, v255, 14
	s_bfe_u32 s58, s2, 0x30003
	s_add_i32 s59, s9, 1
	s_mul_i32 s8, s57, 0x300000
	s_mul_hi_i32 s2, s57, 0x300000
	s_add_u32 s8, s40, s8
	v_lshrrev_b32_e32 v1, 1, v212
	s_addc_u32 s2, s41, s2
	s_mul_i32 s10, s9, 0x600
	v_and_b32_e32 v1, 24, v1
	s_add_u32 s8, s8, s10
	v_lshlrev_b32_e32 v2, 1, v1
	s_addc_u32 s9, s2, 0
	s_mul_i32 s2, s58, 0x300000
	v_lshl_or_b32 v0, v0, 6, v2
	v_lshlrev_b32_e32 v2, 2, v212
	s_add_u32 s0, s0, s2
	v_and_b32_e32 v2, 32, v2
	s_addc_u32 s1, s1, 0
	v_bitop3_b32 v3, v0, s13, v2 bitop3:0xde
	v_bitop3_b32 v143, v0, s14, v2 bitop3:0xde
	s_mov_b32 s13, 0x18000
	s_add_u32 s10, s0, s10
	v_or_b32_e32 v145, s18, v1
	v_lshrrev_b32_e32 v1, 1, v8
	v_mul_lo_u32 v0, v9, s12
	s_addc_u32 s11, s1, 0
	v_mad_u64_u32 v[0:1], s[0:1], v1, s13, v[0:1]
	v_or_b32_e32 v0, v0, v10
	s_mov_b64 s[14:15], 0x180080
	v_add_lshl_u32 v0, v0, v11, 1
	v_mov_b32_e32 v1, v131
	v_lshl_add_u64 v[136:137], v[0:1], 0, s[14:15]
	v_lshrrev_b32_e32 v1, 1, v12
	v_mul_lo_u32 v0, v13, s12
	v_mad_u64_u32 v[0:1], s[0:1], v1, s13, v[0:1]
	s_waitcnt vmcnt(6)
	v_or_b32_e32 v0, v0, v14
	v_add_lshl_u32 v0, v0, v15, 1
	v_mov_b32_e32 v1, v131
	s_movk_i32 s69, 0x60
	v_add_u32_e32 v144, 0xffffe000, v142
	v_lshl_add_u64 v[138:139], v[0:1], 0, s[14:15]
	s_mov_b64 s[0:1], -1
	v_add_u32_e32 v146, s88, v143
	v_add_u32_e32 v147, 0, v3
	v_add_u32_e32 v148, s89, v143
	s_mov_b64 s[12:13], 0x100000
	s_mov_b32 s60, 0x100000
	s_mov_b64 s[14:15], 0x120000
	s_mov_b32 s61, 0x120000
	s_mov_b64 s[18:19], 0x140000
	s_mov_b32 s62, 0x140000
	s_mov_b64 s[22:23], 0x160000
	s_mov_b64 s[24:25], 0x80000
	s_mov_b32 s63, 0x80000
	s_mov_b64 s[26:27], 0x90000
	s_mov_b32 s64, 0x90000
	s_mov_b64 s[28:29], 0xa0000
	s_mov_b32 s65, 0xa0000
	s_mov_b64 s[36:37], 0xb0000
	s_mov_b32 s66, 0xb0000
	s_mov_b32 s2, 0
	s_barrier
	s_mov_b64 s[8:9], s[98:99]
	s_mov_b64 s[10:11], s[100:101]
	s_mov_b32 s69, 12
	s_mov_b32 s2, s59
	s_mov_b32 s98, s68
	s_mov_b32 s68, s58
	s_mov_b32 s58, s98
	s_mov_b32 s98, s67
	s_mov_b32 s67, s57
	s_mov_b32 s57, s98
	s_branch .LBB0_1380

; template <class Epi, class S_t>
; __device__ __forceinline__ void gemm_phase(LAS unsigned char* lds, int lda, int ldb, const S_t& S, const Epi& E) {
;     ...
;         if (!has_next) break;
; #pragma unroll
;         for (int a = 0; a < 2; ++a)
; #pragma unroll
;             for (int b = 0; b < 2; ++b)
; #pragma unroll
;                 for (int m = 0; m < 4; ++m)
; #pragma unroll
;                     for (int n = 0; n < 2; ++n) acc[a][b][m][n] = (f32x4){0.f, 0.f, 0.f, 0.f};
;         cur = nxt; cA = nA; cB = nB; ++ui;
.LBB0_1379:
	s_mov_b64 s[0:1], 0
	s_movk_i32 s69, 0x60
	s_and_b64 vcc, exec, s[38:39]
	s_mov_b32 s2, 0
	s_mov_b32 s68, s58
	s_mov_b32 s67, s57
	s_mov_b64 s[48:49], s[10:11]
	s_mov_b64 s[46:47], s[8:9]
	s_cbranch_vccnz .LBB0_1387
